# wtlast + grid barrier acquire (buffer_inv sc1) issued at arrival instead of after the release is observed
# baseline (speedup 1.0000x reference)
.LBB0_170:
	s_or_b64 exec, exec, s[10:11]
	v_cvt_f32_u32_e32 v5, v3
	s_waitcnt vmcnt(0)
	v_readfirstlane_b32 s8, v4
	v_sub_u32_e32 v4, 0, v3
	v_rcp_iflag_f32_e32 v5, v5
	v_add_u32_e32 v6, s8, v2
	v_mul_f32_e32 v5, 0x4f7ffffe, v5
	v_cvt_u32_f32_e32 v5, v5
	v_mul_lo_u32 v2, v4, v5
	v_mul_hi_u32 v2, v5, v2
	v_add_u32_e32 v2, v5, v2
	v_mul_hi_u32 v2, v6, v2
	v_mul_lo_u32 v4, v2, v3
	v_sub_u32_e32 v4, v6, v4
	v_add_u32_e32 v5, 1, v2
	v_cmp_ge_u32_e32 vcc, v4, v3
	s_nop 1
	v_cndmask_b32_e32 v2, v2, v5, vcc
	v_sub_u32_e32 v5, v4, v3
	v_cndmask_b32_e32 v4, v4, v5, vcc
	v_add_u32_e32 v5, 1, v2
	v_cmp_ge_u32_e32 vcc, v4, v3
	v_add_u32_e32 v4, 1, v6
	s_nop 0
	v_cndmask_b32_e32 v2, v2, v5, vcc
	v_mul_lo_u32 v5, v3, v2
	v_add_u32_e32 v3, v5, v3
	v_cmp_ne_u32_e32 vcc, v4, v3
	s_and_saveexec_b64 s[8:9], vcc
	s_xor_b64 s[8:9], exec, s[8:9]
	s_cbranch_execz .LBB0_184
	s_waitcnt lgkmcnt(0)
	v_mov_b32_e32 v1, 0x2000
	buffer_inv sc1
	global_load_dword v1, v1, s[6:7] offset:1024 sc1
	s_add_u32 s14, s6, 0x2400
	s_addc_u32 s15, s7, 0
	s_waitcnt vmcnt(0)
	v_cmp_eq_u32_e32 vcc, v1, v2
	s_and_saveexec_b64 s[10:11], vcc
	s_cbranch_execz .LBB0_183
	s_add_u32 s12, s46, 0x4200
	s_addc_u32 s13, s47, 0
	s_mov_b32 s30, 1
	s_mov_b64 s[16:17], 0
	v_mov_b32_e32 v1, 0
	s_branch .LBB0_174

.LBB0_183:
	s_or_b64 exec, exec, s[10:11]
	s_waitcnt vmcnt(0)
	s_nop 0
	s_waitcnt vmcnt(0)
.LBB0_184:
	s_andn2_saveexec_b64 s[8:9], s[8:9]
	s_cbranch_execz .LBB0_204
	s_mov_b64 s[8:9], exec
	buffer_wbl2 sc1
	buffer_inv sc1
	s_waitcnt lgkmcnt(0)
	s_waitcnt vmcnt(0)
	v_mbcnt_lo_u32_b32 v2, s8, 0
	v_mbcnt_hi_u32_b32 v2, s9, v2
	v_cmp_eq_u32_e32 vcc, 0, v2
	s_and_saveexec_b64 s[10:11], vcc
	s_cbranch_execz .LBB0_187
	s_bcnt1_i32_b64 s8, s[8:9]
	v_mov_b32_e32 v3, 0x7000
	v_mov_b32_e32 v4, s8
	global_atomic_add v3, v3, v4, s[46:47] offset:1024 sc0

.LBB0_201:
	s_or_b64 exec, exec, s[8:9]
	s_mov_b64 s[8:9], exec
	v_mbcnt_lo_u32_b32 v1, s8, 0
	v_mbcnt_hi_u32_b32 v1, s9, v1
	v_cmp_eq_u32_e32 vcc, 0, v1
	s_waitcnt vmcnt(0)
	s_nop 0
	s_and_saveexec_b64 s[10:11], vcc
	s_cbranch_execz .LBB0_203
	s_bcnt1_i32_b64 s8, s[8:9]
	v_mov_b32_e32 v1, 0x2000
	v_mov_b32_e32 v2, s8
	global_atomic_add v1, v2, s[6:7] offset:1024

.LBB0_265:
	s_or_b64 exec, exec, s[8:9]
	v_cvt_f32_u32_e32 v5, v3
	s_waitcnt vmcnt(0)
	v_readfirstlane_b32 s6, v4
	v_sub_u32_e32 v4, 0, v3
	v_rcp_iflag_f32_e32 v5, v5
	v_add_u32_e32 v6, s6, v2
	v_mul_f32_e32 v5, 0x4f7ffffe, v5
	v_cvt_u32_f32_e32 v5, v5
	v_mul_lo_u32 v2, v4, v5
	v_mul_hi_u32 v2, v5, v2
	v_add_u32_e32 v2, v5, v2
	v_mul_hi_u32 v2, v6, v2
	v_mul_lo_u32 v4, v2, v3
	v_sub_u32_e32 v4, v6, v4
	v_add_u32_e32 v5, 1, v2
	v_cmp_ge_u32_e32 vcc, v4, v3
	s_nop 1
	v_cndmask_b32_e32 v2, v2, v5, vcc
	v_sub_u32_e32 v5, v4, v3
	v_cndmask_b32_e32 v4, v4, v5, vcc
	v_add_u32_e32 v5, 1, v2
	v_cmp_ge_u32_e32 vcc, v4, v3
	v_add_u32_e32 v4, 1, v6
	s_nop 0
	v_cndmask_b32_e32 v2, v2, v5, vcc
	v_mul_lo_u32 v5, v3, v2
	v_add_u32_e32 v3, v5, v3
	v_cmp_ne_u32_e32 vcc, v4, v3
	s_and_saveexec_b64 s[6:7], vcc
	s_xor_b64 s[6:7], exec, s[6:7]
	s_cbranch_execz .LBB0_279
	s_waitcnt lgkmcnt(0)
	v_mov_b32_e32 v1, 0x2000
	buffer_inv sc1
	global_load_dword v1, v1, s[4:5] offset:1024 sc1
	s_add_u32 s12, s4, 0x2400
	s_addc_u32 s13, s5, 0
	s_waitcnt vmcnt(0)
	v_cmp_eq_u32_e32 vcc, v1, v2
	s_and_saveexec_b64 s[8:9], vcc
	s_cbranch_execz .LBB0_278
	s_add_u32 s10, s46, 0x4200
	s_addc_u32 s11, s47, 0
	s_mov_b32 s26, 1
	s_mov_b64 s[14:15], 0
	v_mov_b32_e32 v1, 0
	s_branch .LBB0_269

.LBB0_278:
	s_or_b64 exec, exec, s[8:9]
	s_waitcnt vmcnt(0)
	s_nop 0
	s_waitcnt vmcnt(0)
.LBB0_279:
	s_andn2_saveexec_b64 s[6:7], s[6:7]
	s_cbranch_execz .LBB0_299
	s_mov_b64 s[6:7], exec
	buffer_wbl2 sc1
	buffer_inv sc1
	s_waitcnt lgkmcnt(0)
	s_waitcnt vmcnt(0)
	v_mbcnt_lo_u32_b32 v2, s6, 0
	v_mbcnt_hi_u32_b32 v2, s7, v2
	v_cmp_eq_u32_e32 vcc, 0, v2
	s_and_saveexec_b64 s[8:9], vcc
	s_cbranch_execz .LBB0_282
	s_bcnt1_i32_b64 s6, s[6:7]
	v_mov_b32_e32 v3, 0x7000
	v_mov_b32_e32 v4, s6
	global_atomic_add v3, v3, v4, s[46:47] offset:1024 sc0

.LBB0_296:
	s_or_b64 exec, exec, s[6:7]
	s_mov_b64 s[6:7], exec
	v_mbcnt_lo_u32_b32 v1, s6, 0
	v_mbcnt_hi_u32_b32 v1, s7, v1
	v_cmp_eq_u32_e32 vcc, 0, v1
	s_waitcnt vmcnt(0)
	s_nop 0
	s_and_saveexec_b64 s[8:9], vcc
	s_cbranch_execz .LBB0_298
	s_bcnt1_i32_b64 s6, s[6:7]
	v_mov_b32_e32 v1, 0x2000
	v_mov_b32_e32 v2, s6
	global_atomic_add v1, v2, s[4:5] offset:1024

.LBB0_384:
	s_or_b64 exec, exec, s[14:15]
	v_cvt_f32_u32_e32 v6, v4
	s_waitcnt vmcnt(0)
	v_readfirstlane_b32 s4, v5
	v_sub_u32_e32 v5, 0, v4
	v_rcp_iflag_f32_e32 v6, v6
	v_add_u32_e32 v7, s4, v3
	v_mul_f32_e32 v6, 0x4f7ffffe, v6
	v_cvt_u32_f32_e32 v6, v6
	v_mul_lo_u32 v3, v5, v6
	v_mul_hi_u32 v3, v6, v3
	v_add_u32_e32 v3, v6, v3
	v_mul_hi_u32 v3, v7, v3
	v_mul_lo_u32 v5, v3, v4
	v_sub_u32_e32 v5, v7, v5
	v_add_u32_e32 v6, 1, v3
	v_cmp_ge_u32_e32 vcc, v5, v4
	s_nop 1
	v_cndmask_b32_e32 v3, v3, v6, vcc
	v_sub_u32_e32 v6, v5, v4
	v_cndmask_b32_e32 v5, v5, v6, vcc
	v_add_u32_e32 v6, 1, v3
	v_cmp_ge_u32_e32 vcc, v5, v4
	v_add_u32_e32 v5, 1, v7
	s_nop 0
	v_cndmask_b32_e32 v3, v3, v6, vcc
	v_mul_lo_u32 v6, v4, v3
	v_add_u32_e32 v4, v6, v4
	v_cmp_ne_u32_e32 vcc, v5, v4
	s_and_saveexec_b64 s[14:15], vcc
	s_xor_b64 s[14:15], exec, s[14:15]
	s_cbranch_execz .LBB0_398
	v_readlane_b32 s4, v253, 40
	v_readlane_b32 s5, v253, 41
	s_waitcnt lgkmcnt(0)
	s_nop 3
	buffer_inv sc1
	global_load_dword v2, v99, s[4:5] sc1
	s_waitcnt vmcnt(0)
	v_cmp_eq_u32_e32 vcc, v2, v3
	s_and_saveexec_b64 s[20:21], vcc
	s_cbranch_execz .LBB0_397
	s_mov_b32 s18, 1
	s_mov_b64 s[30:31], 0
	s_branch .LBB0_388

.LBB0_397:
	s_or_b64 exec, exec, s[20:21]
	s_waitcnt vmcnt(0)
	s_nop 0
	s_waitcnt vmcnt(0)
.LBB0_398:
	s_andn2_saveexec_b64 s[14:15], s[14:15]
	s_cbranch_execz .LBB0_418
	s_mov_b64 s[14:15], exec
	buffer_wbl2 sc1
	buffer_inv sc1
	s_waitcnt lgkmcnt(0)
	s_waitcnt vmcnt(0)
	v_mbcnt_lo_u32_b32 v3, s14, 0
	v_mbcnt_hi_u32_b32 v3, s15, v3
	v_cmp_eq_u32_e32 vcc, 0, v3
	s_and_saveexec_b64 s[20:21], vcc
	s_cbranch_execz .LBB0_401
	s_bcnt1_i32_b64 s4, s[14:15]
	v_mov_b32_e32 v4, s4
	v_readlane_b32 s4, v253, 42
	v_readlane_b32 s5, v253, 43
	s_nop 4
	global_atomic_add v4, v99, v4, s[4:5] sc0

.LBB0_415:
	s_or_b64 exec, exec, s[14:15]
	s_mov_b64 s[14:15], exec
	v_mbcnt_lo_u32_b32 v2, s14, 0
	v_mbcnt_hi_u32_b32 v2, s15, v2
	v_cmp_eq_u32_e32 vcc, 0, v2
	s_waitcnt vmcnt(0)
	s_nop 0
	s_and_saveexec_b64 s[20:21], vcc
	s_cbranch_execz .LBB0_417
	s_bcnt1_i32_b64 s4, s[14:15]
	v_mov_b32_e32 v2, s4
	v_readlane_b32 s4, v253, 40
	v_readlane_b32 s5, v253, 41
	s_nop 4
	global_atomic_add v99, v2, s[4:5]

.LBB0_523:
	s_or_b64 exec, exec, s[10:11]
	v_cvt_f32_u32_e32 v6, v4
	s_waitcnt vmcnt(0)
	v_readfirstlane_b32 s4, v5
	v_sub_u32_e32 v5, 0, v4
	v_rcp_iflag_f32_e32 v6, v6
	v_add_u32_e32 v7, s4, v3
	v_mul_f32_e32 v6, 0x4f7ffffe, v6
	v_cvt_u32_f32_e32 v6, v6
	v_mul_lo_u32 v3, v5, v6
	v_mul_hi_u32 v3, v6, v3
	v_add_u32_e32 v3, v6, v3
	v_mul_hi_u32 v3, v7, v3
	v_mul_lo_u32 v5, v3, v4
	v_sub_u32_e32 v5, v7, v5
	v_add_u32_e32 v6, 1, v3
	v_cmp_ge_u32_e32 vcc, v5, v4
	s_nop 1
	v_cndmask_b32_e32 v3, v3, v6, vcc
	v_sub_u32_e32 v6, v5, v4
	v_cndmask_b32_e32 v5, v5, v6, vcc
	v_add_u32_e32 v6, 1, v3
	v_cmp_ge_u32_e32 vcc, v5, v4
	v_add_u32_e32 v5, 1, v7
	s_nop 0
	v_cndmask_b32_e32 v3, v3, v6, vcc
	v_mul_lo_u32 v6, v4, v3
	v_add_u32_e32 v4, v6, v4
	v_cmp_ne_u32_e32 vcc, v5, v4
	s_and_saveexec_b64 s[10:11], vcc
	s_xor_b64 s[10:11], exec, s[10:11]
	s_cbranch_execz .LBB0_537
	v_readlane_b32 s4, v253, 40
	v_readlane_b32 s5, v253, 41
	s_waitcnt lgkmcnt(0)
	s_nop 3
	buffer_inv sc1
	global_load_dword v2, v99, s[4:5] sc1
	s_waitcnt vmcnt(0)
	v_cmp_eq_u32_e32 vcc, v2, v3
	s_and_saveexec_b64 s[12:13], vcc
	s_cbranch_execz .LBB0_536
	s_mov_b32 s27, 1
	s_mov_b64 s[14:15], 0
	s_branch .LBB0_527

.LBB0_536:
	s_or_b64 exec, exec, s[12:13]
	s_waitcnt vmcnt(0)
	s_nop 0
	s_waitcnt vmcnt(0)
.LBB0_537:
	s_andn2_saveexec_b64 s[10:11], s[10:11]
	s_cbranch_execz .LBB0_557
	s_mov_b64 s[10:11], exec
	buffer_wbl2 sc1
	buffer_inv sc1
	s_waitcnt lgkmcnt(0)
	s_waitcnt vmcnt(0)
	v_mbcnt_lo_u32_b32 v3, s10, 0
	v_mbcnt_hi_u32_b32 v3, s11, v3
	v_cmp_eq_u32_e32 vcc, 0, v3
	s_and_saveexec_b64 s[12:13], vcc
	s_cbranch_execz .LBB0_540
	s_bcnt1_i32_b64 s4, s[10:11]
	v_mov_b32_e32 v4, s4
	v_readlane_b32 s4, v253, 42
	v_readlane_b32 s5, v253, 43
	s_nop 4
	global_atomic_add v4, v99, v4, s[4:5] sc0

.LBB0_554:
	s_or_b64 exec, exec, s[10:11]
	s_mov_b64 s[10:11], exec
	v_mbcnt_lo_u32_b32 v2, s10, 0
	v_mbcnt_hi_u32_b32 v2, s11, v2
	v_cmp_eq_u32_e32 vcc, 0, v2
	s_waitcnt vmcnt(0)
	s_nop 0
	s_and_saveexec_b64 s[12:13], vcc
	s_cbranch_execz .LBB0_556
	s_bcnt1_i32_b64 s4, s[10:11]
	v_mov_b32_e32 v2, s4
	v_readlane_b32 s4, v253, 40
	v_readlane_b32 s5, v253, 41
	s_nop 4
	global_atomic_add v99, v2, s[4:5]

.LBB0_954:
	s_or_b64 exec, exec, s[12:13]
	v_cvt_f32_u32_e32 v6, v4
	s_waitcnt vmcnt(0)
	v_readfirstlane_b32 s4, v5
	v_sub_u32_e32 v5, 0, v4
	v_rcp_iflag_f32_e32 v6, v6
	v_add_u32_e32 v7, s4, v3
	v_mul_f32_e32 v6, 0x4f7ffffe, v6
	v_cvt_u32_f32_e32 v6, v6
	v_mul_lo_u32 v3, v5, v6
	v_mul_hi_u32 v3, v6, v3
	v_add_u32_e32 v3, v6, v3
	v_mul_hi_u32 v3, v7, v3
	v_mul_lo_u32 v5, v3, v4
	v_sub_u32_e32 v5, v7, v5
	v_add_u32_e32 v6, 1, v3
	v_cmp_ge_u32_e32 vcc, v5, v4
	s_nop 1
	v_cndmask_b32_e32 v3, v3, v6, vcc
	v_sub_u32_e32 v6, v5, v4
	v_cndmask_b32_e32 v5, v5, v6, vcc
	v_add_u32_e32 v6, 1, v3
	v_cmp_ge_u32_e32 vcc, v5, v4
	v_add_u32_e32 v5, 1, v7
	s_nop 0
	v_cndmask_b32_e32 v3, v3, v6, vcc
	v_mul_lo_u32 v6, v4, v3
	v_add_u32_e32 v4, v6, v4
	v_cmp_ne_u32_e32 vcc, v5, v4
	s_and_saveexec_b64 s[4:5], vcc
	s_xor_b64 s[12:13], exec, s[4:5]
	s_cbranch_execz .LBB0_968
	v_readlane_b32 s4, v253, 40
	v_readlane_b32 s5, v253, 41
	s_waitcnt lgkmcnt(0)
	s_nop 3
	buffer_inv sc1
	global_load_dword v2, v99, s[4:5] sc1
	s_waitcnt vmcnt(0)
	v_cmp_eq_u32_e32 vcc, v2, v3
	s_and_saveexec_b64 s[14:15], vcc
	s_cbranch_execz .LBB0_967
	s_mov_b32 s27, 1
	s_mov_b64 s[20:21], 0
	s_branch .LBB0_958

.LBB0_967:
	s_or_b64 exec, exec, s[14:15]
	s_waitcnt vmcnt(0)
	s_nop 0
	s_waitcnt vmcnt(0)
.LBB0_968:
	s_andn2_saveexec_b64 s[4:5], s[12:13]
	s_cbranch_execz .LBB0_988
	s_mov_b64 s[12:13], exec
	buffer_wbl2 sc1
	buffer_inv sc1
	s_waitcnt lgkmcnt(0)
	s_waitcnt vmcnt(0)
	v_mbcnt_lo_u32_b32 v3, s12, 0
	v_mbcnt_hi_u32_b32 v3, s13, v3
	v_cmp_eq_u32_e32 vcc, 0, v3
	s_and_saveexec_b64 s[14:15], vcc
	s_cbranch_execz .LBB0_971
	s_bcnt1_i32_b64 s4, s[12:13]
	v_mov_b32_e32 v4, s4
	v_readlane_b32 s4, v253, 42
	v_readlane_b32 s5, v253, 43
	s_nop 4
	global_atomic_add v4, v99, v4, s[4:5] sc0

.LBB0_985:
	s_or_b64 exec, exec, s[12:13]
	s_mov_b64 s[12:13], exec
	v_mbcnt_lo_u32_b32 v2, s12, 0
	v_mbcnt_hi_u32_b32 v2, s13, v2
	v_cmp_eq_u32_e32 vcc, 0, v2
	s_waitcnt vmcnt(0)
	s_nop 0
	s_and_saveexec_b64 s[14:15], vcc
	s_cbranch_execz .LBB0_987
	s_bcnt1_i32_b64 s4, s[12:13]
	v_mov_b32_e32 v2, s4
	v_readlane_b32 s4, v253, 40
	v_readlane_b32 s5, v253, 41
	s_nop 4
	global_atomic_add v99, v2, s[4:5]

.LBB0_1047:
	s_or_b64 exec, exec, s[10:11]
	v_cvt_f32_u32_e32 v6, v4
	s_waitcnt vmcnt(0)
	v_readfirstlane_b32 s4, v5
	v_sub_u32_e32 v5, 0, v4
	v_rcp_iflag_f32_e32 v6, v6
	v_add_u32_e32 v7, s4, v3
	v_mul_f32_e32 v6, 0x4f7ffffe, v6
	v_cvt_u32_f32_e32 v6, v6
	v_mul_lo_u32 v3, v5, v6
	v_mul_hi_u32 v3, v6, v3
	v_add_u32_e32 v3, v6, v3
	v_mul_hi_u32 v3, v7, v3
	v_mul_lo_u32 v5, v3, v4
	v_sub_u32_e32 v5, v7, v5
	v_add_u32_e32 v6, 1, v3
	v_cmp_ge_u32_e32 vcc, v5, v4
	s_nop 1
	v_cndmask_b32_e32 v3, v3, v6, vcc
	v_sub_u32_e32 v6, v5, v4
	v_cndmask_b32_e32 v5, v5, v6, vcc
	v_add_u32_e32 v6, 1, v3
	v_cmp_ge_u32_e32 vcc, v5, v4
	v_add_u32_e32 v5, 1, v7
	s_nop 0
	v_cndmask_b32_e32 v3, v3, v6, vcc
	v_mul_lo_u32 v6, v4, v3
	v_add_u32_e32 v4, v6, v4
	v_cmp_ne_u32_e32 vcc, v5, v4
	s_and_saveexec_b64 s[4:5], vcc
	s_xor_b64 s[10:11], exec, s[4:5]
	s_cbranch_execz .LBB0_1061
	v_readlane_b32 s4, v253, 40
	v_readlane_b32 s5, v253, 41
	s_waitcnt lgkmcnt(0)
	s_nop 3
	buffer_inv sc1
	global_load_dword v2, v99, s[4:5] sc1
	s_waitcnt vmcnt(0)
	v_cmp_eq_u32_e32 vcc, v2, v3
	s_and_saveexec_b64 s[14:15], vcc
	s_cbranch_execz .LBB0_1060
	s_mov_b32 s27, 1
	s_mov_b64 s[20:21], 0
	s_branch .LBB0_1051

.LBB0_1061:
	s_andn2_saveexec_b64 s[4:5], s[10:11]
	s_cbranch_execz .LBB0_1081
	s_mov_b64 s[10:11], exec
	buffer_wbl2 sc1
	buffer_inv sc1
	s_waitcnt lgkmcnt(0)
	s_waitcnt vmcnt(0)
	v_mbcnt_lo_u32_b32 v3, s10, 0
	v_mbcnt_hi_u32_b32 v3, s11, v3
	v_cmp_eq_u32_e32 vcc, 0, v3
	s_and_saveexec_b64 s[14:15], vcc
	s_cbranch_execz .LBB0_1064
	s_bcnt1_i32_b64 s4, s[10:11]
	v_mov_b32_e32 v4, s4
	v_readlane_b32 s4, v253, 42
	v_readlane_b32 s5, v253, 43
	s_nop 4
	global_atomic_add v4, v99, v4, s[4:5] sc0

.LBB0_1078:
	s_or_b64 exec, exec, s[10:11]
	s_mov_b64 s[10:11], exec
	v_mbcnt_lo_u32_b32 v2, s10, 0
	v_mbcnt_hi_u32_b32 v2, s11, v2
	v_cmp_eq_u32_e32 vcc, 0, v2
	s_waitcnt vmcnt(0)
	s_nop 0
	s_and_saveexec_b64 s[14:15], vcc
	s_cbranch_execz .LBB0_1080
	s_bcnt1_i32_b64 s4, s[10:11]
	v_mov_b32_e32 v2, s4
	v_readlane_b32 s4, v253, 40
	v_readlane_b32 s5, v253, 41
	s_nop 4
	global_atomic_add v99, v2, s[4:5]

.LBB0_1233:
	s_or_b64 exec, exec, s[14:15]
	v_cvt_f32_u32_e32 v6, v4
	s_waitcnt vmcnt(0)
	v_readfirstlane_b32 s4, v5
	v_sub_u32_e32 v5, 0, v4
	v_rcp_iflag_f32_e32 v6, v6
	v_add_u32_e32 v7, s4, v3
	v_mul_f32_e32 v6, 0x4f7ffffe, v6
	v_cvt_u32_f32_e32 v6, v6
	v_mul_lo_u32 v3, v5, v6
	v_mul_hi_u32 v3, v6, v3
	v_add_u32_e32 v3, v6, v3
	v_mul_hi_u32 v3, v7, v3
	v_mul_lo_u32 v5, v3, v4
	v_sub_u32_e32 v5, v7, v5
	v_add_u32_e32 v6, 1, v3
	v_cmp_ge_u32_e32 vcc, v5, v4
	s_nop 1
	v_cndmask_b32_e32 v3, v3, v6, vcc
	v_sub_u32_e32 v6, v5, v4
	v_cndmask_b32_e32 v5, v5, v6, vcc
	v_add_u32_e32 v6, 1, v3
	v_cmp_ge_u32_e32 vcc, v5, v4
	v_add_u32_e32 v5, 1, v7
	s_nop 0
	v_cndmask_b32_e32 v3, v3, v6, vcc
	v_mul_lo_u32 v6, v4, v3
	v_add_u32_e32 v4, v6, v4
	v_cmp_ne_u32_e32 vcc, v5, v4
	s_and_saveexec_b64 s[4:5], vcc
	s_xor_b64 s[14:15], exec, s[4:5]
	s_cbranch_execz .LBB0_1264
	v_readlane_b32 s4, v253, 40
	v_readlane_b32 s5, v253, 41
	s_waitcnt lgkmcnt(0)
	s_nop 3
	buffer_inv sc1
	global_load_dword v2, v99, s[4:5] sc1
	s_waitcnt vmcnt(0)
	v_cmp_eq_u32_e32 vcc, v2, v3
	s_and_saveexec_b64 s[20:21], vcc
	s_cbranch_execz .LBB0_1263
	s_mov_b32 s18, 1
	s_mov_b64 s[26:27], 0
	s_branch .LBB0_1237

.LBB0_1250:
	s_or_b64 exec, exec, s[10:11]
	v_cvt_f32_u32_e32 v6, v4
	s_waitcnt vmcnt(0)
	v_readfirstlane_b32 s4, v5
	v_sub_u32_e32 v5, 0, v4
	v_rcp_iflag_f32_e32 v6, v6
	v_add_u32_e32 v7, s4, v3
	v_mul_f32_e32 v6, 0x4f7ffffe, v6
	v_cvt_u32_f32_e32 v6, v6
	v_mul_lo_u32 v3, v5, v6
	v_mul_hi_u32 v3, v6, v3
	v_add_u32_e32 v3, v6, v3
	v_mul_hi_u32 v3, v7, v3
	v_mul_lo_u32 v5, v3, v4
	v_sub_u32_e32 v5, v7, v5
	v_add_u32_e32 v6, 1, v3
	v_cmp_ge_u32_e32 vcc, v5, v4
	s_nop 1
	v_cndmask_b32_e32 v3, v3, v6, vcc
	v_sub_u32_e32 v6, v5, v4
	v_cndmask_b32_e32 v5, v5, v6, vcc
	v_add_u32_e32 v6, 1, v3
	v_cmp_ge_u32_e32 vcc, v5, v4
	v_add_u32_e32 v5, 1, v7
	s_nop 0
	v_cndmask_b32_e32 v3, v3, v6, vcc
	v_mul_lo_u32 v6, v4, v3
	v_add_u32_e32 v4, v6, v4
	v_cmp_ne_u32_e32 vcc, v5, v4
	s_and_saveexec_b64 s[4:5], vcc
	s_xor_b64 s[10:11], exec, s[4:5]
	s_cbranch_execz .LBB0_1281
	v_readlane_b32 s4, v253, 40
	v_readlane_b32 s5, v253, 41
	s_waitcnt lgkmcnt(0)
	s_nop 3
	buffer_inv sc1
	global_load_dword v2, v99, s[4:5] sc1
	s_waitcnt vmcnt(0)
	v_cmp_eq_u32_e32 vcc, v2, v3
	s_and_saveexec_b64 s[12:13], vcc
	s_cbranch_execz .LBB0_1280
	s_mov_b32 s18, 1
	s_mov_b64 s[14:15], 0
	s_branch .LBB0_1254

.LBB0_1264:
	s_andn2_saveexec_b64 s[4:5], s[14:15]
	s_cbranch_execz .LBB0_1301
	s_mov_b64 s[14:15], exec
	buffer_wbl2 sc1
	buffer_inv sc1
	s_waitcnt lgkmcnt(0)
	s_waitcnt vmcnt(0)
	v_mbcnt_lo_u32_b32 v3, s14, 0
	v_mbcnt_hi_u32_b32 v3, s15, v3
	v_cmp_eq_u32_e32 vcc, 0, v3
	s_and_saveexec_b64 s[20:21], vcc
	s_cbranch_execz .LBB0_1267
	s_bcnt1_i32_b64 s4, s[14:15]
	v_mov_b32_e32 v4, s4
	v_readlane_b32 s4, v253, 42
	v_readlane_b32 s5, v253, 43
	s_nop 4
	global_atomic_add v4, v99, v4, s[4:5] sc0

.LBB0_1281:
	s_andn2_saveexec_b64 s[4:5], s[10:11]
	s_cbranch_execz .LBB0_1309
	s_mov_b64 s[10:11], exec
	buffer_wbl2 sc1
	buffer_inv sc1
	s_waitcnt lgkmcnt(0)
	s_waitcnt vmcnt(0)
	v_mbcnt_lo_u32_b32 v3, s10, 0
	v_mbcnt_hi_u32_b32 v3, s11, v3
	v_cmp_eq_u32_e32 vcc, 0, v3
	s_and_saveexec_b64 s[12:13], vcc
	s_cbranch_execz .LBB0_1284
	s_bcnt1_i32_b64 s4, s[10:11]
	v_mov_b32_e32 v4, s4
	v_readlane_b32 s4, v253, 42
	v_readlane_b32 s5, v253, 43
	s_nop 4
	global_atomic_add v4, v99, v4, s[4:5] sc0
